# weight-tile loops of phase 0, phase 6 slack and phase 8 slack all software-pipelined by rotation (generic tool)
# speedup vs baseline: 1.0036x; 1.0036x over previous
; __device__ __forceinline__ unsigned cvt_pk_bf16(float lo, float hi) { unsigned r; asm volatile("v_cvt_pk_bf16_f32 %0, %1, %2" : "=v"(r) : "v"(lo), "v"(hi)); return r; }
; __device__ __forceinline__ int early_tile(int k) { if (k < 1472) return k; k -= 1472; if (k < 704) return 2880 + k; k -= 704; if (k < 256) return 4288 + k; k -= 256; if (k < 64) return 4800 + k; k -= 64; return 4928 + k; }
; __device__ __forceinline__ void transpose_tile(const float* src, int ldsrc, int k0, int n0, bf16_t* dst, int ldd, const float* gain, int rowmode, float* T) {
;     ...
;     { const int n = tid >> 3, k8 = (tid & 7) * 8; const float* tp = T + n * 65 + k8; u32x4 w;
;         w.x = cvt_pk_bf16(tp[0], tp[1]); w.y = cvt_pk_bf16(tp[2], tp[3]); w.z = cvt_pk_bf16(tp[4], tp[5]); w.w = cvt_pk_bf16(tp[6], tp[7]);
;         const int nn = n0 + n; int row;
;         if (rowmode == 1) row = (nn >> 7) * 256 + (nn & 127);
;         else if (rowmode == 2) row = (nn >> 7) * 256 + 128 + (nn & 127);
;         else if (rowmode == 3) row = nn < 1024 ? nn : (nn < 2048 ? nn + 1024 : nn - 1024);
;         else row = nn;
;         *(u32x4*)(dst + (size_t)row * ldd + k0 + k8) = w; }
; __device__ __forceinline__ void prep_weights(const Params& P, float* T) {
;     ...
;         if (blockIdx.x < 16) { for (int k = N_EARLY - 128 + blockIdx.x; k < N_EARLY; k += 16) weight_tile(P, early_tile(k), T); }
;         else { for (int k = blockIdx.x - 16; k < N_EARLY - 128; k += 240) weight_tile(P, early_tile(k), T); }
.Lrot0_save:
	v_mov_b32_e32 v200, s20
	v_mov_b32_e32 v201, s36
	v_mov_b32_e32 v202, s37
	v_mov_b32_e32 v204, s34
	v_mov_b32_e32 v205, s35
	s_lshl_b32 s100, s41, 1
	v_mov_b32_e32 v206, s100
	v_mov_b32_e32 v207, 0
	s_mov_b32 s97, s74
	s_bitset1_b32 s32, 0
	s_addk_i32 s3, 0xf0
	s_addk_i32 s63, 0xf0
	s_cmpk_gt_i32 s72, 0xb4f
	s_cbranch_scc1 .Lrot0_last
	s_branch .LBB0_1190

; __device__ __forceinline__ unsigned cvt_pk_bf16(float lo, float hi) { unsigned r; asm volatile("v_cvt_pk_bf16_f32 %0, %1, %2" : "=v"(r) : "v"(lo), "v"(hi)); return r; }
; __device__ __forceinline__ void transpose_tile(const float* src, int ldsrc, int k0, int n0, bf16_t* dst, int ldd, const float* gain, int rowmode, float* T) {
;     ...
;     { const int n = tid >> 3, k8 = (tid & 7) * 8; const float* tp = T + n * 65 + k8; u32x4 w;
;         w.x = cvt_pk_bf16(tp[0], tp[1]); w.y = cvt_pk_bf16(tp[2], tp[3]); w.z = cvt_pk_bf16(tp[4], tp[5]); w.w = cvt_pk_bf16(tp[6], tp[7]);
;         const int nn = n0 + n; int row;
;         if (rowmode == 1) row = (nn >> 7) * 256 + (nn & 127);
;         else if (rowmode == 2) row = (nn >> 7) * 256 + 128 + (nn & 127);
;         else if (rowmode == 3) row = nn < 1024 ? nn : (nn < 2048 ? nn + 1024 : nn - 1024);
;         else row = nn;
.Lrot0_tail:
	s_mov_b64 s[98:99], -1
	ds_read2_b32 v[136:137], v10 offset1:1
	s_waitcnt lgkmcnt(0)
	v_cvt_pk_bf16_f32 v136, v136, v137
	ds_read2_b32 v[138:139], v10 offset0:2 offset1:3
	s_waitcnt lgkmcnt(0)
	v_cvt_pk_bf16_f32 v137, v138, v139
	ds_read2_b32 v[138:139], v10 offset0:4 offset1:5
	s_waitcnt lgkmcnt(0)
	v_cvt_pk_bf16_f32 v138, v138, v139
	ds_read2_b32 v[150:151], v10 offset0:6 offset1:7
	s_waitcnt lgkmcnt(0)
	v_cvt_pk_bf16_f32 v139, v150, v151
	v_add_u32_e32 v150, v200, v9
	s_cmp_lt_i32 s97, 2
	s_cbranch_scc1 .LBB0_1226
	s_cmp_gt_i32 s97, 2
	s_cbranch_scc0 .LBB0_1223
	v_cmp_gt_u32_e32 vcc, s64, v150
	s_mov_b64 s[98:99], 0
	s_nop 0
	v_cndmask_b32_e32 v151, v12, v13, vcc
	v_cmp_lt_u32_e32 vcc, s65, v150
	s_nop 1
	v_cndmask_b32_e32 v151, 0, v151, vcc
	v_add_u32_e32 v151, v151, v150
.LBB0_1223:
	s_andn2_b64 vcc, exec, s[98:99]
	s_cbranch_vccnz .LBB0_1225
	v_lshlrev_b32_e32 v151, 1, v150
	v_and_b32_e32 v151, 0x3f00, v151
	v_and_b32_e32 v152, 0x7f, v150
	v_or3_b32 v151, v152, v151, s71

; __device__ __forceinline__ void transpose_tile(const float* src, int ldsrc, int k0, int n0, bf16_t* dst, int ldd, const float* gain, int rowmode, float* T) {
;     ...
;         if (rowmode == 1) row = (nn >> 7) * 256 + (nn & 127);
;         else if (rowmode == 2) row = (nn >> 7) * 256 + 128 + (nn & 127);
;         else if (rowmode == 3) row = nn < 1024 ? nn : (nn < 2048 ? nn + 1024 : nn - 1024);
;         else row = nn;
;         *(u32x4*)(dst + (size_t)row * ldd + k0 + k8) = w; }
;     __syncthreads();
.LBB0_1226:
	s_andn2_b64 vcc, exec, s[98:99]
	s_cbranch_vccnz .LBB0_1189
	s_cmp_lg_u32 s97, 1
	s_cbranch_scc1 .LBB0_1188
	v_lshlrev_b32_e32 v151, 1, v150
	v_and_b32_e32 v150, 0x7f, v150
	v_and_or_b32 v150, v151, s70, v150
	s_branch .LBB0_1188
.LBB0_1188:
	v_mov_b32_e32 v151, v150
.LBB0_1189:
	v_mad_u64_u32 v[152:153], s[98:99], v201, v151, 0
	v_mov_b32_e32 v150, v153
	v_mad_u64_u32 v[150:151], s[98:99], v202, v151, v[150:151]
	v_mov_b32_e32 v153, v150
	v_lshl_add_u64 v[150:151], v[152:153], 1, v[204:205]
	v_lshl_add_u64 v[150:151], v[150:151], 0, v[206:207]
	v_lshl_add_u64 v[150:151], v[150:151], 0, v[6:7]
	global_store_dwordx4 v[150:151], v[136:139], off
	s_barrier
	s_bitcmp1_b32 s32, 1
	s_cbranch_scc1 .LBB0_1230
	s_branch .Lrot0_mid

; __device__ __forceinline__ int defer_tile(int k) { if (k < 1408) return 1472 + k; k -= 1408; if (k < 704) return 3584 + k; k -= 704; if (k < 256) return 4544 + k; k -= 256; if (k < 64) return 4864 + k; k -= 64; return 5696 + k; }
; #define PHASE(k, ...) if (EN(k) && lo <= (k) && (k) < hi) { constexpr bool dup_ = false; (void)dup_; __VA_ARGS__ if ((k) + 1 < hi) GRID_SYNC(); } if (DUP(k) && lo <= (k) && (k) < hi) { constexpr bool dup_ = true; (void)dup_; __VA_ARGS__ GRID_SYNC(); }
; __device__ __forceinline__ void transpose_tile(const float* src, int ldsrc, int k0, int n0, bf16_t* dst, int ldd, const float* gain, int rowmode, float* T) {
;     const int tid = threadIdx.x;
;     { const int kk = tid >> 4, n4 = (tid & 15) * 4; const float* gp = gain ? gain : src;
;         const f32x4 v0 = *(const f32x4*)(src + (size_t)(k0 + kk) * ldsrc + n0 + n4), v1 = *(const f32x4*)(src + (size_t)(k0 + kk + 32) * ldsrc + n0 + n4);
;         float g0 = gp[k0 + kk], g1 = gp[k0 + kk + 32]; if (!gain) { g0 = 1.0f; g1 = 1.0f; }
; __global__ void __launch_bounds__(NT, 2) fwd_kernel(Params P) {
;     ...
;     PHASE(6, gla_g1(P, lds); if (!dup_ && G == 256 && bx >= 64) { __syncthreads(); for (int k = bx - 64; k < N_DEFER; k += 384) weight_tile(P, defer_tile(k), (float*)lds); } )
.LBB0_1978:
	s_cmp_lt_i32 s2, 64
	s_cselect_b64 s[6:7], -1, 0
	s_xor_b64 s[8:9], s[50:51], -1
	s_mov_b64 s[94:95], s[50:51]
	s_or_b64 s[6:7], s[6:7], s[8:9]
	s_mov_b32 s96, s4
	v_readlane_b32 s4, v240, 4
	v_readlane_b32 s50, v240, 2
	s_and_b64 vcc, exec, s[6:7]
	v_readlane_b32 s5, v240, 5
	v_readlane_b32 s51, v240, 3
	s_cbranch_vccnz .LBB0_2019
	s_cmpk_gt_u32 s2, 0xabf
	s_waitcnt vmcnt(0) lgkmcnt(0)
	s_barrier
	s_cbranch_scc1 .LBB0_2019
	s_load_dwordx2 s[6:7], s[0:1], 0xc0
	s_sub_i32 s3, s2, 64
	s_load_dwordx4 s[8:11], s[0:1], 0x30
	s_load_dwordx2 s[16:17], s[0:1], 0x40
	s_load_dwordx2 s[20:21], s[0:1], 0x88
	s_load_dwordx2 s[22:23], s[0:1], 0x50
	s_load_dwordx2 s[24:25], s[0:1], 0x68
	s_load_dwordx2 s[28:29], s[0:1], 0xb0
	s_load_dwordx4 s[12:15], s[0:1], 0xa0
	s_waitcnt lgkmcnt(0)
	s_add_u32 s18, s6, 0x2c88000
	s_addc_u32 s19, s7, 0
	s_add_u32 s26, s6, 0x2680000
	s_addc_u32 s27, s7, 0
	s_add_u32 s8, s8, 0x1000
	s_addc_u32 s9, s9, 0
	s_add_u32 s46, s6, 0x2580000
	s_addc_u32 s47, s7, 0
	s_add_u32 s48, s6, 0x2180000
	s_addc_u32 s49, s7, 0
	s_add_u32 s60, s6, 0x1680000
	v_lshlrev_b32_e32 v0, 2, v210
	v_lshlrev_b32_e32 v2, 3, v210
	s_addc_u32 s61, s7, 0
	v_lshrrev_b32_e32 v8, 4, v210
	v_and_b32_e32 v0, 60, v0
	v_lshrrev_b32_e32 v9, 3, v210
	v_and_b32_e32 v2, 56, v2
	s_add_u32 s62, s6, 0x80000
	v_mov_b32_e32 v5, 0
	v_lshl_add_u32 v1, v8, 2, 0
	v_mul_u32_u24_e32 v3, 0x104, v0
	v_mul_u32_u24_e32 v4, 0x104, v9
	v_lshlrev_b32_e32 v6, 2, v2
	s_addc_u32 s63, s7, 0
	s_mov_b32 s31, 0
	v_add3_u32 v10, 0, v4, v6
	s_add_i32 s30, s2, 0xfffffe40
	s_movk_i32 s64, 0x9c0
	v_lshlrev_b32_e32 v4, 2, v0
	v_add_u32_e32 v11, v1, v3
	s_movk_i32 s65, 0x800
	s_movk_i32 s76, 0x3ff
	s_movk_i32 s77, 0x3f00
	s_movk_i32 s78, 0x80
	v_lshlrev_b32_e32 v6, 1, v2
	v_mov_b32_e32 v7, v5
	v_mov_b32_e32 v12, 0xfffffc00
	v_mov_b32_e32 v13, 0x400
	s_mov_b32 s32, 0
	s_branch .LBB0_1983

; __device__ __forceinline__ int defer_tile(int k) { if (k < 1408) return 1472 + k; k -= 1408; if (k < 704) return 3584 + k; k -= 704; if (k < 256) return 4544 + k; k -= 256; if (k < 64) return 4864 + k; k -= 64; return 5696 + k; }
; #define PHASE(k, ...) if (EN(k) && lo <= (k) && (k) < hi) { constexpr bool dup_ = false; (void)dup_; __VA_ARGS__ if ((k) + 1 < hi) GRID_SYNC(); } if (DUP(k) && lo <= (k) && (k) < hi) { constexpr bool dup_ = true; (void)dup_; __VA_ARGS__ GRID_SYNC(); }
; __device__ __forceinline__ void transpose_tile(const float* src, int ldsrc, int k0, int n0, bf16_t* dst, int ldd, const float* gain, int rowmode, float* T) {
;     ...
;     { const int kk = tid >> 4, n4 = (tid & 15) * 4; const float* gp = gain ? gain : src;
;         const f32x4 v0 = *(const f32x4*)(src + (size_t)(k0 + kk) * ldsrc + n0 + n4), v1 = *(const f32x4*)(src + (size_t)(k0 + kk + 32) * ldsrc + n0 + n4);
;         float g0 = gp[k0 + kk], g1 = gp[k0 + kk + 32]; if (!gain) { g0 = 1.0f; g1 = 1.0f; }
; #pragma unroll
;         for (int j = 0; j < 4; ++j) { T[(n4 + j) * 65 + kk] = v0[j] * g0; T[(n4 + j) * 65 + kk + 32] = v1[j] * g1; } }
;     __syncthreads();
; __global__ void __launch_bounds__(NT, 2) fwd_kernel(Params P) {
;     ...
;     PHASE(6, gla_g1(P, lds); if (!dup_ && G == 256 && bx >= 64) { __syncthreads(); for (int k = bx - 64; k < N_DEFER; k += 384) weight_tile(P, defer_tile(k), (float*)lds); } )
.LBB0_2008:
	s_and_b32 s41, 0xffff, s30
	v_cvt_f32_u32_e32 v0, s41
	s_and_b32 s41, s82, 0xffff
	v_cvt_f32_u32_e32 v1, s41
	v_rcp_iflag_f32_e32 v2, v0
	s_nop 0
	v_mul_f32_e32 v2, v1, v2
	v_trunc_f32_e32 v2, v2
	v_cvt_u32_f32_e32 v3, v2
	v_fma_f32 v1, -v2, v0, v1
	v_cmp_ge_f32_e64 s[44:45], |v1|, v0
	s_cmp_lg_u64 s[44:45], 0
	v_readfirstlane_b32 s41, v3
	s_addc_u32 s41, s41, 0
	s_and_b32 s44, s41, 0xffff
	s_mul_i32 s41, s41, s30
	s_sub_i32 s30, s82, s41
	s_lshl_b32 s41, s44, 6
	s_lshl_b32 s44, s30, 6
	s_cmp_eq_u64 s[42:43], 0
	v_or_b32_e32 v14, s41, v8
	s_cselect_b64 s[66:67], -1, 0
	s_and_b64 s[82:83], s[66:67], exec
	v_add_u32_e32 v2, 32, v14
	s_cselect_b32 s43, s37, s43
	s_cselect_b32 s42, s36, s42
	v_mul_hi_u32_u24_e32 v1, s40, v14
	v_mul_u32_u24_e32 v0, s40, v14
	s_lshl_b32 s30, s30, 8
	v_mul_hi_u32_u24_e32 v3, s40, v2
	v_mul_u32_u24_e32 v2, s40, v2
	v_lshl_add_u64 v[0:1], v[0:1], 2, s[36:37]
	s_and_b32 s30, s30, 0x3ff00
	v_lshl_add_u64 v[2:3], v[2:3], 2, s[36:37]
	v_lshl_add_u64 v[0:1], v[0:1], 0, s[30:31]
	v_lshl_add_u64 v[2:3], v[2:3], 0, s[30:31]
	v_lshlrev_b32_e32 v14, 2, v14
	v_lshl_add_u64 v[0:1], v[0:1], 0, v[4:5]
	global_load_dword v18, v14, s[42:43]
	global_load_dword v19, v14, s[42:43] offset:128
	v_lshl_add_u64 v[14:15], v[2:3], 0, v[4:5]
	global_load_dwordx4 v[0:3], v[0:1], off
	s_nop 0
	global_load_dwordx4 v[14:17], v[14:15], off
	s_bitcmp1_b32 s32, 0
	s_cbranch_scc1 .Lrot6_tail
	s_and_b32 s30, 0xffff, s44
	s_cmp_lt_i32 s80, 2
	s_mov_b64 s[36:37], -1
	s_waitcnt vmcnt(3)
	v_cndmask_b32_e64 v18, v18, 1.0, s[66:67]
	s_waitcnt vmcnt(2)
	v_cndmask_b32_e64 v19, v19, 1.0, s[66:67]
	s_waitcnt vmcnt(1)
	v_mul_f32_e32 v0, v0, v18
	s_waitcnt vmcnt(0)
	v_mul_f32_e32 v14, v14, v19
	v_mul_f32_e32 v1, v1, v18
	v_mul_f32_e32 v15, v15, v19
	v_mul_f32_e32 v2, v2, v18
	v_mul_f32_e32 v16, v16, v19
	v_mul_f32_e32 v3, v3, v18
	v_mul_f32_e32 v17, v17, v19
	ds_write2_b32 v11, v0, v14 offset1:32
	ds_write2_b32 v11, v1, v15 offset0:65 offset1:97
	ds_write2_b32 v11, v2, v16 offset0:130 offset1:162
	ds_write2_b32 v11, v3, v17 offset0:195 offset1:227
	s_waitcnt lgkmcnt(0)
	s_barrier
	s_branch .Lrot6_save
.Lrot6_mid:
	s_and_b32 s30, 0xffff, s44
	s_cmp_lt_i32 s80, 2
	s_mov_b64 s[36:37], -1
	s_waitcnt vmcnt(4)
	v_cndmask_b32_e64 v18, v18, 1.0, s[66:67]
	s_waitcnt vmcnt(3)
	v_cndmask_b32_e64 v19, v19, 1.0, s[66:67]
	s_waitcnt vmcnt(2)
	v_mul_f32_e32 v0, v0, v18
	s_waitcnt vmcnt(1)
	v_mul_f32_e32 v14, v14, v19
	v_mul_f32_e32 v1, v1, v18
	v_mul_f32_e32 v15, v15, v19
	v_mul_f32_e32 v2, v2, v18
	v_mul_f32_e32 v16, v16, v19
	v_mul_f32_e32 v3, v3, v18
	v_mul_f32_e32 v17, v17, v19
	ds_write2_b32 v11, v0, v14 offset1:32
	ds_write2_b32 v11, v1, v15 offset0:65 offset1:97
	ds_write2_b32 v11, v2, v16 offset0:130 offset1:162
	ds_write2_b32 v11, v3, v17 offset0:195 offset1:227
	s_waitcnt lgkmcnt(0)
	s_barrier
.Lrot6_save:
	v_mov_b32_e32 v200, s30
	v_mov_b32_e32 v201, s38
	v_mov_b32_e32 v202, s39
	v_mov_b32_e32 v204, s34
	v_mov_b32_e32 v205, s35
	s_lshl_b32 s100, s41, 1
	v_mov_b32_e32 v206, s100
	v_mov_b32_e32 v207, 0
	s_mov_b32 s97, s80
	s_bitset1_b32 s32, 0
	s_add_i32 s30, s79, 0xffffff40
	s_cmpk_lt_i32 s79, 0x900
	s_cselect_b32 s30, s79, s30
	s_add_i32 s3, s30, 0x180
	s_cmpk_lt_i32 s79, 0x9c0
	s_cbranch_scc0 .Lrot6_last
	s_branch .LBB0_1983

; __device__ __forceinline__ unsigned cvt_pk_bf16(float lo, float hi) { unsigned r; asm volatile("v_cvt_pk_bf16_f32 %0, %1, %2" : "=v"(r) : "v"(lo), "v"(hi)); return r; }
; __device__ __forceinline__ void transpose_tile(const float* src, int ldsrc, int k0, int n0, bf16_t* dst, int ldd, const float* gain, int rowmode, float* T) {
;     ...
;     { const int n = tid >> 3, k8 = (tid & 7) * 8; const float* tp = T + n * 65 + k8; u32x4 w;
;         w.x = cvt_pk_bf16(tp[0], tp[1]); w.y = cvt_pk_bf16(tp[2], tp[3]); w.z = cvt_pk_bf16(tp[4], tp[5]); w.w = cvt_pk_bf16(tp[6], tp[7]);
;         const int nn = n0 + n; int row;
;         if (rowmode == 1) row = (nn >> 7) * 256 + (nn & 127);
;         else if (rowmode == 2) row = (nn >> 7) * 256 + 128 + (nn & 127);
;         else if (rowmode == 3) row = nn < 1024 ? nn : (nn < 2048 ? nn + 1024 : nn - 1024);
;         else row = nn;
.Lrot6_tail:
	s_mov_b64 s[98:99], -1
	ds_read2_b32 v[136:137], v10 offset1:1
	s_waitcnt lgkmcnt(0)
	v_cvt_pk_bf16_f32 v136, v136, v137
	ds_read2_b32 v[138:139], v10 offset0:2 offset1:3
	s_waitcnt lgkmcnt(0)
	v_cvt_pk_bf16_f32 v137, v138, v139
	ds_read2_b32 v[138:139], v10 offset0:4 offset1:5
	s_waitcnt lgkmcnt(0)
	v_cvt_pk_bf16_f32 v138, v138, v139
	ds_read2_b32 v[150:151], v10 offset0:6 offset1:7
	s_waitcnt lgkmcnt(0)
	v_cvt_pk_bf16_f32 v139, v150, v151
	v_add_u32_e32 v150, v200, v9
	s_cmp_lt_i32 s97, 2
	s_cbranch_scc1 .LBB0_2014
	s_cmp_gt_i32 s97, 2
	s_cbranch_scc0 .LBB0_2011
	v_cmp_gt_u32_e32 vcc, s65, v150
	s_mov_b64 s[98:99], 0
	s_nop 0
	v_cndmask_b32_e32 v151, v12, v13, vcc
	v_cmp_lt_u32_e32 vcc, s76, v150
	s_nop 1
	v_cndmask_b32_e32 v151, 0, v151, vcc
	v_add_u32_e32 v151, v151, v150
.LBB0_2011:
	s_andn2_b64 vcc, exec, s[98:99]
	s_cbranch_vccnz .LBB0_2013
	v_lshlrev_b32_e32 v151, 1, v150
	v_and_b32_e32 v151, 0x3f00, v151
	v_and_b32_e32 v152, 0x7f, v150
	v_or3_b32 v151, v152, v151, s78

; __device__ __forceinline__ void transpose_tile(const float* src, int ldsrc, int k0, int n0, bf16_t* dst, int ldd, const float* gain, int rowmode, float* T) {
;     ...
;         if (rowmode == 1) row = (nn >> 7) * 256 + (nn & 127);
;         else if (rowmode == 2) row = (nn >> 7) * 256 + 128 + (nn & 127);
;         else if (rowmode == 3) row = nn < 1024 ? nn : (nn < 2048 ? nn + 1024 : nn - 1024);
;         else row = nn;
;         *(u32x4*)(dst + (size_t)row * ldd + k0 + k8) = w; }
.LBB0_2014:
	s_andn2_b64 vcc, exec, s[98:99]
	s_cbranch_vccnz .LBB0_1982
	s_cmp_lg_u32 s97, 1
	s_cbranch_scc1 .LBB0_1981
	v_lshlrev_b32_e32 v151, 1, v150
	v_and_b32_e32 v150, 0x7f, v150
	v_and_or_b32 v150, v151, s77, v150
	s_branch .LBB0_1981

; __device__ __forceinline__ int defer_tile(int k) { if (k < 1408) return 1472 + k; k -= 1408; if (k < 704) return 3584 + k; k -= 704; if (k < 256) return 4544 + k; k -= 256; if (k < 64) return 4864 + k; k -= 64; return 5696 + k; }
; #define PHASE(k, ...) if (EN(k) && lo <= (k) && (k) < hi) { constexpr bool dup_ = false; (void)dup_; __VA_ARGS__ if ((k) + 1 < hi) GRID_SYNC(); } if (DUP(k) && lo <= (k) && (k) < hi) { constexpr bool dup_ = true; (void)dup_; __VA_ARGS__ GRID_SYNC(); }
; __device__ __forceinline__ void transpose_tile(const float* src, int ldsrc, int k0, int n0, bf16_t* dst, int ldd, const float* gain, int rowmode, float* T) {
;     const int tid = threadIdx.x;
;     { const int kk = tid >> 4, n4 = (tid & 15) * 4; const float* gp = gain ? gain : src;
;         const f32x4 v0 = *(const f32x4*)(src + (size_t)(k0 + kk) * ldsrc + n0 + n4), v1 = *(const f32x4*)(src + (size_t)(k0 + kk + 32) * ldsrc + n0 + n4);
;         float g0 = gp[k0 + kk], g1 = gp[k0 + kk + 32]; if (!gain) { g0 = 1.0f; g1 = 1.0f; }
; __global__ void __launch_bounds__(NT, 2) fwd_kernel(Params P) {
;     ...
;     PHASE(8, gla_g3(P, lds); if (!dup_ && G == 256 && bx >= 64) { __syncthreads(); for (int k = 192 + bx - 64; k < N_DEFER; k += 384) weight_tile(P, defer_tile(k), (float*)lds); } )
.LBB0_2181:
	s_cmp_lt_i32 s2, 64
	s_cselect_b64 s[6:7], -1, 0
	s_xor_b64 s[8:9], s[94:95], -1
	s_or_b64 s[6:7], s[6:7], s[8:9]
	s_and_b64 vcc, exec, s[6:7]
	s_cbranch_vccnz .LBB0_2222
	s_cmpk_gt_u32 s2, 0x9ff
	s_barrier
	s_cbranch_scc1 .LBB0_2222
	s_add_i32 s46, s2, 0x80
	s_add_u32 s6, s44, 0x2c88000
	s_addc_u32 s7, s45, 0
	s_add_u32 s24, s44, 0x2680000
	s_load_dwordx4 s[8:11], s[0:1], 0x30
	s_load_dwordx2 s[16:17], s[0:1], 0x40
	s_load_dwordx2 s[18:19], s[0:1], 0x88
	s_load_dwordx2 s[20:21], s[0:1], 0x50
	s_load_dwordx2 s[22:23], s[0:1], 0x68
	s_addc_u32 s25, s45, 0
	s_waitcnt lgkmcnt(0)
	s_add_u32 s8, s8, 0x1000
	s_addc_u32 s9, s9, 0
	s_add_u32 s47, s44, 0x2580000
	s_addc_u32 s48, s45, 0
	s_add_u32 s49, s44, 0x2180000
	s_load_dwordx2 s[26:27], s[0:1], 0xb0
	s_load_dwordx4 s[12:15], s[0:1], 0xa0
	s_addc_u32 s60, s45, 0
	s_add_u32 s61, s44, 0x1680000
	s_waitcnt vmcnt(7)
	v_lshlrev_b32_e32 v0, 2, v210
	v_lshlrev_b32_e32 v2, 3, v210
	s_addc_u32 s62, s45, 0
	v_and_b32_e32 v0, 60, v0
	s_waitcnt vmcnt(5)
	v_lshrrev_b32_e32 v8, 3, v210
	v_and_b32_e32 v2, 56, v2
	s_add_u32 s63, s44, 0x80000
	v_mov_b32_e32 v5, 0
	v_lshl_add_u32 v1, v102, 2, 0
	v_mul_u32_u24_e32 v3, 0x104, v0
	v_mul_u32_u24_e32 v4, 0x104, v8
	v_lshlrev_b32_e32 v6, 2, v2
	s_movk_i32 s3, 0x80
	s_addc_u32 s64, s45, 0
	s_mov_b32 s29, 0
	v_add3_u32 v9, 0, v4, v6
	s_movk_i32 s65, 0x9c0
	v_lshlrev_b32_e32 v4, 2, v0
	v_add_u32_e32 v10, v1, v3
	s_movk_i32 s76, 0x800
	s_movk_i32 s77, 0x3ff
	s_movk_i32 s78, 0x3f00
	v_lshlrev_b32_e32 v6, 1, v2
	v_mov_b32_e32 v7, v5
	v_mov_b32_e32 v11, 0xfffffc00
	s_waitcnt vmcnt(4)
	v_mov_b32_e32 v12, 0x400
	s_mov_b32 s32, 0
	s_branch .LBB0_2186

; __device__ __forceinline__ int defer_tile(int k) { if (k < 1408) return 1472 + k; k -= 1408; if (k < 704) return 3584 + k; k -= 704; if (k < 256) return 4544 + k; k -= 256; if (k < 64) return 4864 + k; k -= 64; return 5696 + k; }
; #define PHASE(k, ...) if (EN(k) && lo <= (k) && (k) < hi) { constexpr bool dup_ = false; (void)dup_; __VA_ARGS__ if ((k) + 1 < hi) GRID_SYNC(); } if (DUP(k) && lo <= (k) && (k) < hi) { constexpr bool dup_ = true; (void)dup_; __VA_ARGS__ GRID_SYNC(); }
; __device__ __forceinline__ void transpose_tile(const float* src, int ldsrc, int k0, int n0, bf16_t* dst, int ldd, const float* gain, int rowmode, float* T) {
;     ...
;     { const int kk = tid >> 4, n4 = (tid & 15) * 4; const float* gp = gain ? gain : src;
;         const f32x4 v0 = *(const f32x4*)(src + (size_t)(k0 + kk) * ldsrc + n0 + n4), v1 = *(const f32x4*)(src + (size_t)(k0 + kk + 32) * ldsrc + n0 + n4);
;         float g0 = gp[k0 + kk], g1 = gp[k0 + kk + 32]; if (!gain) { g0 = 1.0f; g1 = 1.0f; }
; #pragma unroll
;         for (int j = 0; j < 4; ++j) { T[(n4 + j) * 65 + kk] = v0[j] * g0; T[(n4 + j) * 65 + kk + 32] = v1[j] * g1; } }
;     __syncthreads();
; __global__ void __launch_bounds__(NT, 2) fwd_kernel(Params P) {
;     ...
;     PHASE(8, gla_g3(P, lds); if (!dup_ && G == 256 && bx >= 64) { __syncthreads(); for (int k = 192 + bx - 64; k < N_DEFER; k += 384) weight_tile(P, defer_tile(k), (float*)lds); } )
.LBB0_2211:
	s_and_b32 s39, 0xffff, s28
	v_cvt_f32_u32_e32 v0, s39
	s_and_b32 s39, s81, 0xffff
	v_cvt_f32_u32_e32 v1, s39
	v_rcp_iflag_f32_e32 v2, v0
	s_nop 0
	v_mul_f32_e32 v2, v1, v2
	v_trunc_f32_e32 v2, v2
	v_cvt_u32_f32_e32 v3, v2
	v_fma_f32 v1, -v2, v0, v1
	v_cmp_ge_f32_e64 s[42:43], |v1|, v0
	s_cmp_lg_u64 s[42:43], 0
	v_readfirstlane_b32 s39, v3
	s_addc_u32 s39, s39, 0
	s_and_b32 s42, s39, 0xffff
	s_mul_i32 s39, s39, s28
	s_sub_i32 s28, s81, s39
	s_lshl_b32 s39, s42, 6
	s_lshl_b32 s42, s28, 6
	s_cmp_eq_u64 s[40:41], 0
	v_or_b32_e32 v13, s39, v102
	s_cselect_b64 s[66:67], -1, 0
	s_and_b64 s[80:81], s[66:67], exec
	v_add_u32_e32 v2, 32, v13
	s_cselect_b32 s41, s35, s41
	s_cselect_b32 s40, s34, s40
	v_mul_hi_u32_u24_e32 v1, s38, v13
	v_mul_u32_u24_e32 v0, s38, v13
	s_lshl_b32 s28, s28, 8
	v_mul_hi_u32_u24_e32 v3, s38, v2
	v_mul_u32_u24_e32 v2, s38, v2
	v_lshl_add_u64 v[0:1], v[0:1], 2, s[34:35]
	s_and_b32 s28, s28, 0x3ff00
	v_lshl_add_u64 v[2:3], v[2:3], 2, s[34:35]
	v_lshl_add_u64 v[0:1], v[0:1], 0, s[28:29]
	v_lshl_add_u64 v[2:3], v[2:3], 0, s[28:29]
	v_lshlrev_b32_e32 v13, 2, v13
	v_lshl_add_u64 v[0:1], v[0:1], 0, v[4:5]
	global_load_dword v18, v13, s[40:41]
	s_nop 0
	global_load_dword v13, v13, s[40:41] offset:128
	v_lshl_add_u64 v[14:15], v[2:3], 0, v[4:5]
	global_load_dwordx4 v[0:3], v[0:1], off
	s_nop 0
	global_load_dwordx4 v[14:17], v[14:15], off
	s_bitcmp1_b32 s32, 0
	s_cbranch_scc1 .Lrot8_tail
	s_and_b32 s28, 0xffff, s42
	s_cmp_lt_i32 s79, 2
	s_mov_b64 s[34:35], -1
	s_waitcnt vmcnt(3)
	v_cndmask_b32_e64 v18, v18, 1.0, s[66:67]
	s_waitcnt vmcnt(2)
	v_cndmask_b32_e64 v13, v13, 1.0, s[66:67]
	s_waitcnt vmcnt(1)
	v_mul_f32_e32 v0, v0, v18
	s_waitcnt vmcnt(0)
	v_mul_f32_e32 v14, v14, v13
	v_mul_f32_e32 v1, v1, v18
	v_mul_f32_e32 v15, v15, v13
	v_mul_f32_e32 v2, v2, v18
	v_mul_f32_e32 v16, v16, v13
	v_mul_f32_e32 v3, v3, v18
	v_mul_f32_e32 v13, v17, v13
	ds_write2_b32 v10, v0, v14 offset1:32
	ds_write2_b32 v10, v1, v15 offset0:65 offset1:97
	ds_write2_b32 v10, v2, v16 offset0:130 offset1:162
	ds_write2_b32 v10, v3, v13 offset0:195 offset1:227
	s_waitcnt lgkmcnt(0)
	s_barrier
	s_branch .Lrot8_save
.Lrot8_mid:
	s_and_b32 s28, 0xffff, s42
	s_cmp_lt_i32 s79, 2
	s_mov_b64 s[34:35], -1
	s_waitcnt vmcnt(4)
	v_cndmask_b32_e64 v18, v18, 1.0, s[66:67]
	s_waitcnt vmcnt(3)
	v_cndmask_b32_e64 v13, v13, 1.0, s[66:67]
	s_waitcnt vmcnt(2)
	v_mul_f32_e32 v0, v0, v18
	s_waitcnt vmcnt(1)
	v_mul_f32_e32 v14, v14, v13
	v_mul_f32_e32 v1, v1, v18
	v_mul_f32_e32 v15, v15, v13
	v_mul_f32_e32 v2, v2, v18
	v_mul_f32_e32 v16, v16, v13
	v_mul_f32_e32 v3, v3, v18
	v_mul_f32_e32 v13, v17, v13
	ds_write2_b32 v10, v0, v14 offset1:32
	ds_write2_b32 v10, v1, v15 offset0:65 offset1:97
	ds_write2_b32 v10, v2, v16 offset0:130 offset1:162
	ds_write2_b32 v10, v3, v13 offset0:195 offset1:227
	s_waitcnt lgkmcnt(0)
	s_barrier
.Lrot8_save:
	v_mov_b32_e32 v200, s28
	v_mov_b32_e32 v201, s36
	v_mov_b32_e32 v202, s37
	v_mov_b32_e32 v204, s30
	v_mov_b32_e32 v205, s31
	s_lshl_b32 s100, s39, 1
	v_mov_b32_e32 v206, s100
	v_mov_b32_e32 v207, 0
	s_mov_b32 s97, s79
	s_bitset1_b32 s32, 0
	s_add_i32 s28, s46, 0x180
	s_cmpk_lt_i32 s46, 0x840
	s_mov_b32 s46, s28
	s_cbranch_scc0 .Lrot8_last
	s_branch .LBB0_2186

; __device__ __forceinline__ unsigned cvt_pk_bf16(float lo, float hi) { unsigned r; asm volatile("v_cvt_pk_bf16_f32 %0, %1, %2" : "=v"(r) : "v"(lo), "v"(hi)); return r; }
; __device__ __forceinline__ void transpose_tile(const float* src, int ldsrc, int k0, int n0, bf16_t* dst, int ldd, const float* gain, int rowmode, float* T) {
;     ...
;     { const int n = tid >> 3, k8 = (tid & 7) * 8; const float* tp = T + n * 65 + k8; u32x4 w;
;         w.x = cvt_pk_bf16(tp[0], tp[1]); w.y = cvt_pk_bf16(tp[2], tp[3]); w.z = cvt_pk_bf16(tp[4], tp[5]); w.w = cvt_pk_bf16(tp[6], tp[7]);
;         const int nn = n0 + n; int row;
;         if (rowmode == 1) row = (nn >> 7) * 256 + (nn & 127);
;         else if (rowmode == 2) row = (nn >> 7) * 256 + 128 + (nn & 127);
;         else if (rowmode == 3) row = nn < 1024 ? nn : (nn < 2048 ? nn + 1024 : nn - 1024);
;         else row = nn;
.Lrot8_tail:
	s_mov_b64 s[98:99], -1
	ds_read2_b32 v[136:137], v9 offset1:1
	s_waitcnt lgkmcnt(0)
	v_cvt_pk_bf16_f32 v136, v136, v137
	ds_read2_b32 v[138:139], v9 offset0:2 offset1:3
	s_waitcnt lgkmcnt(0)
	v_cvt_pk_bf16_f32 v137, v138, v139
	ds_read2_b32 v[138:139], v9 offset0:4 offset1:5
	s_waitcnt lgkmcnt(0)
	v_cvt_pk_bf16_f32 v138, v138, v139
	ds_read2_b32 v[150:151], v9 offset0:6 offset1:7
	v_add_u32_e32 v149, v200, v8
	s_waitcnt lgkmcnt(0)
	v_cvt_pk_bf16_f32 v139, v150, v151
	s_cmp_lt_i32 s97, 2
	s_cbranch_scc1 .LBB0_2217
	s_cmp_gt_i32 s97, 2
	s_cbranch_scc0 .LBB0_2214
	v_cmp_gt_u32_e32 vcc, s76, v149
	s_mov_b64 s[98:99], 0
	s_nop 0
	v_cndmask_b32_e32 v150, v11, v12, vcc
	v_cmp_lt_u32_e32 vcc, s77, v149
	s_nop 1
	v_cndmask_b32_e32 v150, 0, v150, vcc
	v_add_u32_e32 v150, v150, v149
.LBB0_2214:
	s_andn2_b64 vcc, exec, s[98:99]
	s_cbranch_vccnz .LBB0_2216
	v_lshlrev_b32_e32 v150, 1, v149
	v_and_b32_e32 v150, 0x3f00, v150
	v_and_b32_e32 v151, 0x7f, v149
	v_or3_b32 v150, v151, v150, s3

; __device__ __forceinline__ void transpose_tile(const float* src, int ldsrc, int k0, int n0, bf16_t* dst, int ldd, const float* gain, int rowmode, float* T) {
;     ...
;         if (rowmode == 1) row = (nn >> 7) * 256 + (nn & 127);
;         else if (rowmode == 2) row = (nn >> 7) * 256 + 128 + (nn & 127);
;         else if (rowmode == 3) row = nn < 1024 ? nn : (nn < 2048 ? nn + 1024 : nn - 1024);
;         else row = nn;
;         *(u32x4*)(dst + (size_t)row * ldd + k0 + k8) = w; }
;     __syncthreads();
.LBB0_2217:
	s_andn2_b64 vcc, exec, s[98:99]
	s_cbranch_vccnz .LBB0_2185
	s_cmp_lg_u32 s97, 1
	s_cbranch_scc1 .LBB0_2184
	v_lshlrev_b32_e32 v150, 1, v149
	v_and_b32_e32 v149, 0x7f, v149
	v_and_or_b32 v149, v150, s78, v149
	s_branch .LBB0_2184
.LBB0_2184:
	v_mov_b32_e32 v150, v149
.LBB0_2185:
	v_mad_u64_u32 v[152:153], s[98:99], v201, v150, 0
	v_mov_b32_e32 v154, v153
	v_mad_u64_u32 v[150:151], s[98:99], v202, v150, v[154:155]
	v_mov_b32_e32 v153, v150
	v_lshl_add_u64 v[150:151], v[152:153], 1, v[204:205]
	v_lshl_add_u64 v[150:151], v[150:151], 0, v[206:207]
	v_lshl_add_u64 v[150:151], v[150:151], 0, v[6:7]
	global_store_dwordx4 v[150:151], v[136:139], off
	s_barrier
	s_bitcmp1_b32 s32, 1
	s_cbranch_scc1 .LBB0_2222
	s_branch .Lrot8_mid
